# reversed the unit order of the MLP down-projection GEMM within each XCD chunk so it starts on the panels the up-projection wrote last (cache reuse across the phase boundary)
# speedup vs baseline: 1.0067x; 1.0067x over previous
;     __device__ bool next(int i, Unit& u) const {
;         const long L = (long)i * G + c; if (L >= nwg) return false;
;         int wgid = (int)L; { const int q = nwg / NXCD, r = nwg % NXCD, xcd = wgid % NXCD, off = wgid / NXCD; wgid = (xcd < r ? xcd * (q + 1) : r * (q + 1) + (xcd - r) * q) + off; }
;         const int nig = WGM * nN, gid = wgid / nig, fm = gid * WGM, gsz = (nM - fm) < WGM ? (nM - fm) : WGM;
;         u.pm = fm + ((wgid % nig) % gsz); u.pn = (wgid % nig) / gsz; u.ko = 0; return true;
.LBB0_1104:
	s_ashr_i32 s4, s10, 3
	s_sub_i32 s4, 0x7f, s4
	s_add_i32 s4, s12, s4
	s_ashr_i32 s5, s4, 31
	s_lshr_b32 s5, s5, 27
	s_add_i32 s5, s4, s5
	s_ashr_i32 s10, s5, 5
	s_and_b32 s5, s5, 0xffe0
	s_sub_i32 s4, s4, s5
	s_bfe_i32 s5, s4, 0x80000
	s_bfe_u32 s5, s5, 0x3000c
	s_add_i32 s5, s4, s5
	s_bfe_i32 s11, s5, 0x80000
	s_and_b32 s5, s5, 0xf8
	s_sub_i32 s4, s4, s5
	s_lshl_b32 s10, s10, 3
	s_sext_i32_i16 s11, s11
	s_sext_i32_i8 s4, s4
	s_add_i32 s16, s10, s4
	s_ashr_i32 s90, s11, 3

;     __device__ bool next(int i, Unit& u) const {
;         const long L = (long)i * G + c; if (L >= nwg) return false;
;         int wgid = (int)L; { const int q = nwg / NXCD, r = nwg % NXCD, xcd = wgid % NXCD, off = wgid / NXCD; wgid = (xcd < r ? xcd * (q + 1) : r * (q + 1) + (xcd - r) * q) + off; }
;         const int nig = WGM * nN, gid = wgid / nig, fm = gid * WGM, gsz = (nM - fm) < WGM ? (nM - fm) : WGM;
;         u.pm = fm + ((wgid % nig) % gsz); u.pn = (wgid % nig) / gsz; u.ko = 0; return true;
.LBB0_1116:
	s_ashr_i32 s4, s7, 3
	s_sub_i32 s4, 0x7f, s4
	s_add_i32 s4, s20, s4
	s_ashr_i32 s5, s4, 31
	s_lshr_b32 s5, s5, 27
	s_add_i32 s5, s4, s5
	s_ashr_i32 s6, s5, 5
	s_lshl_b32 s6, s6, 3
	s_sub_i32 s7, 0x100, s6
	s_min_i32 s7, s7, 8
	s_abs_i32 s20, s7
	v_cvt_f32_u32_e32 v0, s20
	s_sub_i32 s22, 0, s20
	s_andn2_b32 s5, s5, 31
	s_sub_i32 s5, s4, s5
	v_rcp_iflag_f32_e32 v0, v0
	s_abs_i32 s4, s5
	s_xor_b32 s21, s5, s7
	s_ashr_i32 s21, s21, 31
	v_mul_f32_e32 v0, 0x4f7ffffe, v0
	v_cvt_u32_f32_e32 v0, v0
	s_nop 0
	v_readfirstlane_b32 s23, v0
	s_mul_i32 s22, s22, s23
	s_mul_hi_u32 s22, s23, s22
	s_add_i32 s23, s23, s22
	s_mul_hi_u32 s22, s4, s23
	s_mul_i32 s23, s22, s20
	s_sub_i32 s4, s4, s23
	s_add_i32 s24, s22, 1
	s_sub_i32 s23, s4, s20
	s_cmp_ge_u32 s4, s20
	s_cselect_b32 s22, s24, s22
	s_cselect_b32 s4, s23, s4
	s_add_i32 s23, s22, 1
	s_cmp_ge_u32 s4, s20
	s_cselect_b32 s4, s23, s22
	s_xor_b32 s4, s4, s21
	s_sub_i32 s4, s4, s21
	s_mul_i32 s7, s4, s7
	s_sub_i32 s5, s5, s7
	s_add_i32 s84, s6, s5
